# speedup vs baseline: 1.0319x; 1.0319x over previous
; __device__ __forceinline__ void attn_dense_body(const bf16_t* __restrict__ Qb, const bf16_t* __restrict__ Kh, const bf16_t* __restrict__ Vh,
;                                                 float* __restrict__ Ob, int seq, char* lds, LAS unsigned char* lds3, const int tid) {
;     const int wid = tid >> 6, lane = tid & 63, r32 = lane & 31, hi = lane >> 5, half = wid >> 2;
;     const int wid_s = __builtin_amdgcn_readfirstlane(wid);
;     bf16_t* V_lds = (bf16_t*)lds; bf16_t* K_lds = (bf16_t*)(lds + K_OFF);
;     float* al_l = (float*)(lds + WS_OFF) + wid * 64 + 32;
;     float l_reg = 0; f32x16 o[8] = {}; f32x16 nm = {}; bf16x8 qr[8];
;     const __amdgpu_buffer_rsrc_t rsQ = __builtin_amdgcn_make_buffer_rsrc((void*)Qb, 0, 0x7fffffff, 0x00020000);
;     const __amdgpu_buffer_rsrc_t rsK = __builtin_amdgcn_make_buffer_rsrc((void*)Kh, 0, 0x7fffffff, 0x00020000);
;     const __amdgpu_buffer_rsrc_t rsV = __builtin_amdgcn_make_buffer_rsrc((void*)Vh, 0, 0x7fffffff, 0x00020000);
;     { const unsigned qoffB = (unsigned)((wid * QBLK + r32) * LDQ + hi * 8) * 2u;
; #pragma unroll
;       for (int d0 = 0; d0 < 8; ++d0) { const u32x4 w = __builtin_amdgcn_raw_buffer_load_b128(rsQ, qoffB + d0 * 32, 0, 0); qr[d0] = *reinterpret_cast<const bf16x8*>(&w); } }
;     const int l4 = lane >> 4;
;     const unsigned kg0 = (unsigned)((8 * wid + l4) * 256 + (((lane & 15) ^ l4) * 16)), kg1 = (kg0 ^ 64u) + 1024u;
;     const int kk = 8 * wid + ((lane >> 2) & 7), ksrc = (kk & ~0xC) | ((kk & 4) << 1) | ((kk & 8) >> 1);
;     const unsigned vg0 = (unsigned)(ksrc * 512 + (lane >> 5) * 64 + (lane & 3) * 16);
;     LAS unsigned char* kdst = lds3 + K_OFF + wid_s * 2048;
;     LAS unsigned char* vdst = lds3 + wid_s * 4096;
;     const int vb0 = (int)(uintptr_t)V_lds + v_rd_base(lane);
; __device__ __forceinline__ void attn_phase(const int tid, PRef p, int layer, char* lds) {
;     const int a = layer >> 1;
;     const float lam = ((const float*)(p.ws + WS_LAM))[a];
;     const float lam_init = a == 0 ? 0.2f : 0.47071301834358413f;
;     const float om = 1.f - lam_init;
;     const int nitems = 1024 + (layer == 0 ? 16 : 0);
;     const int wid_s = __builtin_amdgcn_readfirstlane(tid >> 6);
;     float* scr = (float*)(p.ws + WS_SCR) + (size_t)blockIdx.x * 131072;
;     const bf16_t* Q = (const bf16_t*)(p.ws + WS_Q);
;     const bf16_t* Kall = (const bf16_t*)(p.ws + WS_K);
.LBB0_202:
	s_andn2_b64 vcc, exec, s[0:1]
	s_cbranch_vccnz .LBB0_365
	v_readlane_b32 s0, v254, 62
	s_cmp_lt_i32 s0, 2
	s_mov_b64 s[0:1], -1
	s_cbranch_scc1 .LBB0_275
	v_readlane_b32 s0, v254, 62
	s_cmp_gt_i32 s0, 2
	s_mov_b64 s[0:1], -1
	s_cbranch_scc0 .LBB0_241
	s_cmp_eq_u32 s58, 0
	s_movk_i32 s0, 0x410
	v_writelane_b32 v255, s48, 0
	v_mbcnt_lo_u32_b32 v0, -1, 0
	v_mbcnt_hi_u32_b32 v0, -1, v0
	s_cselect_b32 s20, s0, 0x400
	s_waitcnt vmcnt(0)
	v_add_u32_e32 v2, s64, v0
	v_writelane_b32 v255, s49, 1
	s_cmp_ge_i32 s83, s20
	v_readfirstlane_b32 s0, v2
	s_cbranch_scc1 .LBB0_240
	s_cmp_lt_u32 s58, 2
	v_readlane_b32 s6, v254, 5
	s_cselect_b64 vcc, -1, 0
	v_readlane_b32 s7, v254, 6
	s_waitcnt lgkmcnt(0)
	s_add_u32 s1, s54, s6
	s_addc_u32 s2, s55, s7
	s_add_u32 s22, s1, 0x30e00000
	s_addc_u32 s23, s2, 0
	s_add_u32 s6, s54, 0x8200000
	s_addc_u32 s11, s55, 0
	v_readlane_b32 s4, v254, 60
	s_add_u32 s21, s54, 0x10400000
	v_readlane_b32 s5, v254, 61
	s_addc_u32 s49, s55, 0
	s_load_dwordx2 s[4:5], s[4:5], 0x70
	s_add_u32 s53, s54, 0x18600000
	v_writelane_b32 v255, s6, 2
	s_addc_u32 s48, s55, 0
	s_add_u32 s36, s54, 0x20800000
	v_readlane_b32 s8, v255, 0
	s_addc_u32 s37, s55, 0
	s_lshl_b32 s50, s8, 8
	s_lshl_b64 s[6:7], s[50:51], 2
	v_readlane_b32 s9, v255, 1
	s_waitcnt lgkmcnt(0)
	s_add_u32 s38, s4, s6
	s_mov_b32 s4, s8
	s_addc_u32 s39, s5, s7
	s_mov_b32 s9, s51
	v_writelane_b32 v255, s4, 0
	v_mov_b32_e32 v3, 0x3925c000
	v_ashrrev_i32_e32 v238, 6, v2
	v_writelane_b32 v255, s5, 1
	s_lshl_b64 s[4:5], s[8:9], 2
	s_add_u32 s4, s54, s4
	s_addc_u32 s5, s55, s5
	global_load_dword v252, v3, s[4:5]
	v_and_b32_e32 v6, 0x3fffffc0, v2
	v_bfe_u32 v8, v2, 2, 2
	v_lshrrev_b32_e32 v9, 1, v2
	v_and_b32_e32 v13, 0xffffff00, v2
	v_cmp_gt_u32_e64 s[4:5], s79, v2
	v_mov_b32_e32 v2, 0x3f077f5a
	v_mov_b32_e32 v14, 0x3f4ccccd
	v_and_b32_e32 v3, 63, v0
	v_bfe_u32 v5, v0, 5, 1
	v_bfe_u32 v7, v0, 4, 2
	v_cndmask_b32_e32 v230, v2, v14, vcc
	v_lshlrev_b32_e32 v14, 3, v238
	v_and_b32_e32 v4, 31, v0
	v_lshlrev_b32_e32 v10, 4, v0
	v_lshlrev_b32_e32 v11, 3, v0
	v_lshlrev_b32_e32 v12, 1, v0
	v_bitop3_b32 v15, v7, v0, 15 bitop3:0x78
	v_cmp_gt_u32_e64 s[8:9], 32, v3
	v_bitop3_b32 v0, v5, v0, 15 bitop3:0x78
	v_or_b32_e32 v3, v14, v7
	s_mov_b32 s10, 0x7ffff0
	v_lshlrev_b32_e32 v231, 4, v5
	v_lshlrev_b32_e32 v17, 6, v5
	v_lshlrev_b32_e32 v5, 4, v15
	v_and_or_b32 v7, v14, s10, v8
	v_lshlrev_b32_e32 v239, 4, v0
	v_lshlrev_b32_e32 v0, 8, v3
	s_movk_i32 s10, 0x440
	v_bitop3_b32 v241, v0, s10, v5 bitop3:0x36
	s_add_u32 s10, s54, 0x10200000
	v_writelane_b32 v255, s10, 3
	s_addc_u32 s68, s55, 0
	s_add_i32 s10, 0, 0x24000
	s_add_i32 s12, 0, 0x18000
	s_cmp_lg_u32 0, -1
	v_lshlrev_b32_e32 v2, 8, v4
	v_lshl_add_u32 v243, v6, 2, s10
	s_cselect_b32 s10, 0, 0
	s_ashr_i32 s0, s0, 1
	v_add_u32_e32 v244, s12, v2
	s_add_i32 s12, s10, 0x18000
	s_and_b32 s40, s0, 0xffffffe0
	v_lshlrev_b32_e32 v16, 2, v238
	s_add_u32 s42, s1, 0x30e40000
	v_and_b32_e32 v9, 8, v9
	v_and_b32_e32 v8, 4, v16
	s_addc_u32 s43, s2, 0
	s_or_b32 s44, s40, 1
	s_or_b32 s46, s40, 2
	s_or_b32 s58, s40, 3
	v_or3_b32 v3, v7, v9, v8
	s_ashr_i32 s41, s40, 31
	s_ashr_i32 s45, s44, 31
	s_ashr_i32 s47, s46, 31
	s_ashr_i32 s59, s58, 31
	v_and_b32_e32 v18, 48, v10
	v_and_b32_e32 v12, 32, v12
	v_or_b32_e32 v240, v0, v5
	v_lshlrev_b32_e32 v0, 9, v3
	v_add_u32_e32 v246, s12, v2
	s_lshl_b64 s[0:1], s[40:41], 8
	s_lshl_b64 s[12:13], s[44:45], 8
	s_lshl_b64 s[14:15], s[46:47], 8
	s_lshl_b64 s[16:17], s[58:59], 8
	s_movk_i32 s2, 0x118
	v_lshlrev_b32_e32 v20, 13, v238
	v_and_b32_e32 v19, 0xc0, v10
	v_or3_b32 v242, v0, v17, v18
	v_and_or_b32 v0, v11, s2, v12
	s_add_u32 s69, s54, 0x3000
	v_and_b32_e32 v232, 0xf0, v10
	v_cmp_eq_u32_e64 s[6:7], s79, v13
	v_or3_b32 v233, v20, v2, v231
	v_lshl_add_u32 v245, v4, 2, v243
	v_add3_u32 v247, v19, s10, v0
	s_addc_u32 s83, s55, 0
	s_lshl_b64 s[72:73], s[0:1], 2
	s_lshl_b64 s[56:57], s[12:13], 2
	s_lshl_b64 s[70:71], s[14:15], 2
	s_waitcnt vmcnt(0)
	v_mov_b32_e32 v253, v252
	s_lshl_b64 s[64:65], s[16:17], 2
	v_xor_b32_e32 v228, 0x80000000, v252
	v_lshlrev_b32_e32 v16, 7, v238
	v_and_b32_e32 v16, 0x80, v16
	v_xor_b32_e32 v240, v240, v16
	v_xor_b32_e32 v241, v241, v16
	v_mbcnt_lo_u32_b32 v2, -1, 0
	v_mbcnt_hi_u32_b32 v2, -1, v2
	v_and_b32_e32 v3, 15, v2
	v_lshrrev_b32_e32 v4, 4, v2
	v_lshlrev_b32_e32 v233, 13, v238
	v_lshl_or_b32 v233, v3, 8, v233
	v_lshl_or_b32 v233, v4, 4, v233
	v_xor_b32_e32 v5, v3, v4
	v_lshlrev_b32_e32 v239, 4, v5
	v_lshlrev_b32_e32 v246, 8, v3
	v_add_u32_e32 v246, 0x18000, v246
	v_lshrrev_b32_e32 v5, 5, v2
	v_lshlrev_b32_e32 v247, 12, v5
	v_bfe_u32 v5, v2, 4, 1
	v_lshl_or_b32 v247, v5, 7, v247
	v_bfe_u32 v5, v2, 2, 2
	v_lshl_or_b32 v247, v5, 5, v247
	v_and_b32_e32 v5, 3, v2
	v_lshl_or_b32 v247, v5, 3, v247
	v_bfe_u32 v5, v2, 1, 3
	v_lshl_add_u32 v5, v238, 3, v5
	v_lshlrev_b32_e32 v242, 9, v5
	v_lshl_or_b32 v242, v4, 5, v242
	v_and_b32_e32 v5, 1, v2
	v_lshl_or_b32 v242, v5, 4, v242
	v_readlane_b32 s2, v254, 57
	s_branch .LBB0_208

; __device__ __forceinline__ void qkt(f32x16& p0, f32x16& p1, const bf16_t* Ks, const bf16x8* qr, int r32, int hi) {
;     p0 = f32x16{}; p1 = f32x16{};
;     const char* k0p = (const char*)Ks + r32 * 256; const char* k1p = k0p + 32 * 256; int sw = (r32 & 7) << 4; const int hb = hi * 16;
;     asm volatile("" : "+v"(sw));
;     ...
;     bf16x8 a0, a1, c0, c1;
;     KF(0, a0, a1);
;     KF(1, c0, c1); SBAR(); KM(0, a0, a1); SBAR();
;     KF(2, a0, a1); SBAR(); KM(1, c0, c1); SBAR();
;     KF(3, c0, c1); SBAR(); KM(2, a0, a1); SBAR();
;     KF(4, a0, a1); SBAR(); KM(3, c0, c1); SBAR();
;     KF(5, c0, c1); SBAR(); KM(4, a0, a1); SBAR();
;     KF(6, a0, a1); SBAR(); KM(5, c0, c1); SBAR();
; __device__ __forceinline__ void attn_dense_body(const bf16_t* __restrict__ Qb, const bf16_t* __restrict__ Kh, const bf16_t* __restrict__ Vh,
;                                                 float* __restrict__ Ob, int seq, char* lds, LAS unsigned char* lds3, const int tid) {
;     ...
;     const __amdgpu_buffer_rsrc_t rsQ = __builtin_amdgcn_make_buffer_rsrc((void*)Qb, 0, 0x7fffffff, 0x00020000);
;     const __amdgpu_buffer_rsrc_t rsK = __builtin_amdgcn_make_buffer_rsrc((void*)Kh, 0, 0x7fffffff, 0x00020000);
;     const __amdgpu_buffer_rsrc_t rsV = __builtin_amdgcn_make_buffer_rsrc((void*)Vh, 0, 0x7fffffff, 0x00020000);
;     { const unsigned qoffB = (unsigned)((wid * QBLK + r32) * LDQ + hi * 8) * 2u;
; #pragma unroll
;       for (int d0 = 0; d0 < 8; ++d0) { const u32x4 w = __builtin_amdgcn_raw_buffer_load_b128(rsQ, qoffB + d0 * 32, 0, 0); qr[d0] = *reinterpret_cast<const bf16x8*>(&w); } }
;     const int l4 = lane >> 4;
;     const unsigned kg0 = (unsigned)((8 * wid + l4) * 256 + (((lane & 15) ^ l4) * 16)), kg1 = (kg0 ^ 64u) + 1024u;
;     const int kk = 8 * wid + ((lane >> 2) & 7), ksrc = (kk & ~0xC) | ((kk & 4) << 1) | ((kk & 8) >> 1);
;     const unsigned vg0 = (unsigned)(ksrc * 512 + (lane >> 5) * 64 + (lane & 3) * 16);
;     LAS unsigned char* kdst = lds3 + K_OFF + wid_s * 2048;
;     LAS unsigned char* vdst = lds3 + wid_s * 4096;
;     const int vb0 = (int)(uintptr_t)V_lds + v_rd_base(lane);
;     ...
;     f32x16 p0, p1; float al; bf16x8 pa0, pa1, pa2, pa3; const int NT = seq / KVBLK;
;     KDMA(0, 0); KDMA(1, 1); VDMA(0, 0);
;     HBAR(0);
;     qkt(p0, p1, K_lds, qr, r32, hi);
;     if (DESYNC && half == 1) { __builtin_amdgcn_s_barrier(); asm volatile("" ::: "memory"); }
.LBB0_215:
	s_mul_i32 s10, s80, s50
	s_add_u32 s84, s34, s10
	s_addc_u32 s10, s35, 0
	s_mul_i32 s18, s50, 0x410000
	s_add_u32 s28, s81, s18
	s_addc_u32 s18, s66, 0
	s_and_b32 s85, s10, 0xffff
	v_readfirstlane_b32 s10, v238
	s_and_b32 s29, s18, 0xffff
	s_lshl_b32 s18, s10, 11
	s_add_i32 s18, s18, 0
	s_add_i32 s96, s18, 0x18000
	s_mov_b32 s24, s28
	s_mov_b32 s25, s29
	s_mov_b32 s26, s86
	s_mov_b32 s27, s87
	v_add_u32_e32 v0, 0x1000, v233
	s_mov_b32 m0, s96
	buffer_load_dwordx4 v[192:195], v233, s[84:87], 0 offen
	buffer_load_dwordx4 v[196:199], v233, s[84:87], 0 offen offset:64
	buffer_load_dwordx4 v240, s[24:27], 0 offen lds
	s_add_i32 m0, s18, 0x18400
	buffer_load_dwordx4 v[200:203], v233, s[84:87], 0 offen offset:128
	s_lshl_b32 s10, s10, 12
	buffer_load_dwordx4 v241, s[24:27], 0 offen lds
	s_add_i32 m0, s18, 0x1c000
	buffer_load_dwordx4 v[204:207], v233, s[84:87], 0 offen offset:192
	s_add_i32 s98, s10, 0
	buffer_load_dwordx4 v240, s[24:27], s74 offen lds
	s_add_i32 m0, s18, 0x1c400
	buffer_load_dwordx4 v[208:211], v0, s[84:87], 0 offen
	buffer_load_dwordx4 v241, s[24:27], s74 offen lds
	s_mov_b32 s18, s30
	s_mov_b32 s19, s31
	s_mov_b32 m0, s98
	buffer_load_dwordx4 v[212:215], v0, s[84:87], 0 offen offset:64
	buffer_load_dwordx4 v242, s[16:19], 0 offen lds
	s_add_i32 m0, s98, 0x400
	buffer_load_dwordx4 v[216:219], v0, s[84:87], 0 offen offset:128
	buffer_load_dwordx4 v242, s[16:19], s60 offen lds
	s_add_i32 m0, s98, 0x800
	buffer_load_dwordx4 v[220:223], v0, s[84:87], 0 offen offset:192
	buffer_load_dwordx4 v242, s[16:19], s79 offen lds
	s_add_i32 m0, s98, 0xc00
	s_nop 0
	buffer_load_dwordx4 v242, s[16:19], s33 offen lds
	s_waitcnt vmcnt(0) lgkmcnt(0)
	s_barrier
	v_add_u32_e32 v0, v239, v246
	v_xad_u32 v15, v239, 64, v246
	v_xad_u32 v231, v239, s60, v246
	s_movk_i32 s18, 0xc0
	v_xad_u32 v232, v239, s18, v246
	ds_read_b128 v[156:159], v0 offset:0
	ds_read_b128 v[224:227], v15 offset:0
	ds_read_b128 v[234:237], v231 offset:0
	ds_read_b128 v[248:251], v232 offset:0
	s_waitcnt lgkmcnt(3)
	v_mfma_f32_16x16x32_bf16 v[160:163], v[156:159], v[192:195], 0
	v_mfma_f32_16x16x32_bf16 v[164:167], v[156:159], v[208:211], 0
	ds_read_b128 v[156:159], v0 offset:4096
	s_waitcnt lgkmcnt(3)
	v_mfma_f32_16x16x32_bf16 v[160:163], v[224:227], v[196:199], v[160:163]
	v_mfma_f32_16x16x32_bf16 v[164:167], v[224:227], v[212:215], v[164:167]
	ds_read_b128 v[224:227], v15 offset:4096
	s_waitcnt lgkmcnt(3)
	v_mfma_f32_16x16x32_bf16 v[160:163], v[234:237], v[200:203], v[160:163]
	v_mfma_f32_16x16x32_bf16 v[164:167], v[234:237], v[216:219], v[164:167]
	ds_read_b128 v[234:237], v231 offset:4096
	s_waitcnt lgkmcnt(3)
	v_mfma_f32_16x16x32_bf16 v[160:163], v[248:251], v[204:207], v[160:163]
	v_mfma_f32_16x16x32_bf16 v[164:167], v[248:251], v[220:223], v[164:167]
	ds_read_b128 v[248:251], v232 offset:4096
	s_waitcnt lgkmcnt(3)
	v_mfma_f32_16x16x32_bf16 v[168:171], v[156:159], v[192:195], 0
	v_mfma_f32_16x16x32_bf16 v[172:175], v[156:159], v[208:211], 0
	ds_read_b128 v[156:159], v0 offset:8192
	s_waitcnt lgkmcnt(3)
	v_mfma_f32_16x16x32_bf16 v[168:171], v[224:227], v[196:199], v[168:171]
	v_mfma_f32_16x16x32_bf16 v[172:175], v[224:227], v[212:215], v[172:175]
	ds_read_b128 v[224:227], v15 offset:8192
	s_waitcnt lgkmcnt(3)
	v_mfma_f32_16x16x32_bf16 v[168:171], v[234:237], v[200:203], v[168:171]
	v_mfma_f32_16x16x32_bf16 v[172:175], v[234:237], v[216:219], v[172:175]
	ds_read_b128 v[234:237], v231 offset:8192
	s_waitcnt lgkmcnt(3)
	v_mfma_f32_16x16x32_bf16 v[168:171], v[248:251], v[204:207], v[168:171]
	v_mfma_f32_16x16x32_bf16 v[172:175], v[248:251], v[220:223], v[172:175]
	ds_read_b128 v[248:251], v232 offset:8192
	s_waitcnt lgkmcnt(3)
	v_mfma_f32_16x16x32_bf16 v[176:179], v[156:159], v[192:195], 0
	v_mfma_f32_16x16x32_bf16 v[180:183], v[156:159], v[208:211], 0
	ds_read_b128 v[156:159], v0 offset:12288
	s_waitcnt lgkmcnt(3)
	v_mfma_f32_16x16x32_bf16 v[176:179], v[224:227], v[196:199], v[176:179]
	v_mfma_f32_16x16x32_bf16 v[180:183], v[224:227], v[212:215], v[180:183]
	ds_read_b128 v[224:227], v15 offset:12288
	s_waitcnt lgkmcnt(3)
	v_mfma_f32_16x16x32_bf16 v[176:179], v[234:237], v[200:203], v[176:179]
	v_mfma_f32_16x16x32_bf16 v[180:183], v[234:237], v[216:219], v[180:183]
	ds_read_b128 v[234:237], v231 offset:12288
	s_waitcnt lgkmcnt(3)
	v_mfma_f32_16x16x32_bf16 v[176:179], v[248:251], v[204:207], v[176:179]
	v_mfma_f32_16x16x32_bf16 v[180:183], v[248:251], v[220:223], v[180:183]
	ds_read_b128 v[248:251], v232 offset:12288
	s_waitcnt lgkmcnt(3)
	v_mfma_f32_16x16x32_bf16 v[184:187], v[156:159], v[192:195], 0
	v_mfma_f32_16x16x32_bf16 v[188:191], v[156:159], v[208:211], 0
	s_waitcnt lgkmcnt(2)
	v_mfma_f32_16x16x32_bf16 v[184:187], v[224:227], v[196:199], v[184:187]
	v_mfma_f32_16x16x32_bf16 v[188:191], v[224:227], v[212:215], v[188:191]
	s_waitcnt lgkmcnt(1)
	v_mfma_f32_16x16x32_bf16 v[184:187], v[234:237], v[200:203], v[184:187]
	v_mfma_f32_16x16x32_bf16 v[188:191], v[234:237], v[216:219], v[188:191]
	s_waitcnt lgkmcnt(0)
	v_mfma_f32_16x16x32_bf16 v[184:187], v[248:251], v[204:207], v[184:187]
	v_mfma_f32_16x16x32_bf16 v[188:191], v[248:251], v[220:223], v[188:191]
	s_and_saveexec_b64 s[18:19], s[6:7]
	s_cbranch_execz .Lat_stag1
	s_barrier
; #define KDMA(t, b) do { const int so_ = (t) * (int)SHM_K; LAS unsigned char* d_ = kdst + (b) * (int)SHM_K; \
;     __builtin_amdgcn_raw_ptr_buffer_load_lds(rsK, (LAS void*)d_, 16, kg0, so_, 0, 0); __builtin_amdgcn_raw_ptr_buffer_load_lds(rsK, (LAS void*)(d_ + 1024), 16, kg1, so_, 0, 0); } while (0)
; __device__ __forceinline__ void partialSM(f32x16& p0, f32x16& p1, f32x16& nm, bool first, float& alpha) {
;     float pmax = p0[0]; for (int r = 1; r < 16; ++r) pmax = fmaxf(pmax, p0[r]); for (int r = 0; r < 16; ++r) pmax = fmaxf(pmax, p1[r]);
;     { auto rr = __builtin_amdgcn_permlane32_swap(__float_as_uint(pmax), __float_as_uint(pmax), false, false);
;       pmax = fmaxf(__uint_as_float(rr[0]), __uint_as_float(rr[1])); }
;     if (__builtin_expect(!first && __all(pmax <= THRL), 1)) { alpha = 1.f; }
; __device__ __forceinline__ void attn_dense_body(const bf16_t* __restrict__ Qb, const bf16_t* __restrict__ Kh, const bf16_t* __restrict__ Vh,
;                                                 float* __restrict__ Ob, int seq, char* lds, LAS unsigned char* lds3, const int tid) {
;     ...
;     float l_reg = 0; f32x16 o[8] = {}; f32x16 nm = {}; bf16x8 qr[8];
;     ...
;     int b = 0, b1 = 1, b2 = 2;
; #pragma unroll 1
;     for (int j = 0; j < NT; ++j) {
;         { const int tk = j + 2 < NT ? j + 2 : NT - 1, tv = j + 1 < NT ? j + 1 : NT - 1; KDMA(tk, b2); VDMA(tv, b1); }
;         partialSM(p0, p1, nm, j == 0, al);
.Lat_stag1:
	s_or_b64 exec, exec, s[18:19]
	v_mov_b32_e32 v16, 0
	v_mov_b32_e32 v17, 0
	v_mov_b32_e32 v18, 0
	v_mov_b32_e32 v19, 0
	v_mov_b32_e32 v20, 0
	v_mov_b32_e32 v21, 0
	v_mov_b32_e32 v22, 0
	v_mov_b32_e32 v23, 0
	v_mov_b32_e32 v24, 0
	v_mov_b32_e32 v25, 0
	v_mov_b32_e32 v26, 0
	v_mov_b32_e32 v27, 0
	v_mov_b32_e32 v28, 0
	v_mov_b32_e32 v29, 0
	v_mov_b32_e32 v30, 0
	v_mov_b32_e32 v31, 0
	v_mov_b32_e32 v32, 0
	v_mov_b32_e32 v33, 0
	v_mov_b32_e32 v34, 0
	v_mov_b32_e32 v35, 0
	v_mov_b32_e32 v36, 0
	v_mov_b32_e32 v37, 0
	v_mov_b32_e32 v38, 0
	v_mov_b32_e32 v39, 0
	v_mov_b32_e32 v40, 0
	v_mov_b32_e32 v41, 0
	v_mov_b32_e32 v42, 0
	v_mov_b32_e32 v43, 0
	v_mov_b32_e32 v44, 0
	v_mov_b32_e32 v45, 0
	v_mov_b32_e32 v46, 0
	v_mov_b32_e32 v47, 0
	v_mov_b32_e32 v48, 0
	v_mov_b32_e32 v49, 0
	v_mov_b32_e32 v50, 0
	v_mov_b32_e32 v51, 0
	v_mov_b32_e32 v52, 0
	v_mov_b32_e32 v53, 0
	v_mov_b32_e32 v54, 0
	v_mov_b32_e32 v55, 0
	v_mov_b32_e32 v56, 0
	v_mov_b32_e32 v57, 0
	v_mov_b32_e32 v58, 0
	v_mov_b32_e32 v59, 0
	v_mov_b32_e32 v60, 0
	v_mov_b32_e32 v61, 0
	v_mov_b32_e32 v62, 0
	v_mov_b32_e32 v63, 0
	v_mov_b32_e32 v64, 0
	v_mov_b32_e32 v65, 0
	v_mov_b32_e32 v66, 0
	v_mov_b32_e32 v67, 0
	v_mov_b32_e32 v68, 0
	v_mov_b32_e32 v69, 0
	v_mov_b32_e32 v70, 0
	v_mov_b32_e32 v71, 0
	v_mov_b32_e32 v72, 0
	v_mov_b32_e32 v73, 0
	v_mov_b32_e32 v74, 0
	v_mov_b32_e32 v75, 0
	v_mov_b32_e32 v76, 0
	v_mov_b32_e32 v77, 0
	v_mov_b32_e32 v78, 0
	v_mov_b32_e32 v79, 0
	v_mov_b32_e32 v80, 0
	v_mov_b32_e32 v81, 0
	v_mov_b32_e32 v82, 0
	v_mov_b32_e32 v83, 0
	v_mov_b32_e32 v84, 0
	v_mov_b32_e32 v85, 0
	v_mov_b32_e32 v86, 0
	v_mov_b32_e32 v87, 0
	v_mov_b32_e32 v88, 0
	v_mov_b32_e32 v89, 0
	v_mov_b32_e32 v90, 0
	v_mov_b32_e32 v91, 0
	v_mov_b32_e32 v92, 0
	v_mov_b32_e32 v93, 0
	v_mov_b32_e32 v94, 0
	v_mov_b32_e32 v95, 0
	v_mov_b32_e32 v96, 0
	v_mov_b32_e32 v97, 0
	v_mov_b32_e32 v98, 0
	v_mov_b32_e32 v99, 0
	v_mov_b32_e32 v100, 0
	v_mov_b32_e32 v101, 0
	v_mov_b32_e32 v102, 0
	v_mov_b32_e32 v103, 0
	v_mov_b32_e32 v104, 0
	v_mov_b32_e32 v105, 0
	v_mov_b32_e32 v106, 0
	v_mov_b32_e32 v107, 0
	v_mov_b32_e32 v108, 0
	v_mov_b32_e32 v109, 0
	v_mov_b32_e32 v110, 0
	v_mov_b32_e32 v111, 0
	v_mov_b32_e32 v112, 0
	v_mov_b32_e32 v113, 0
	v_mov_b32_e32 v114, 0
	v_mov_b32_e32 v115, 0
	v_mov_b32_e32 v116, 0
	v_mov_b32_e32 v117, 0
	v_mov_b32_e32 v118, 0
	v_mov_b32_e32 v119, 0
	v_mov_b32_e32 v120, 0
	v_mov_b32_e32 v121, 0
	v_mov_b32_e32 v122, 0
	v_mov_b32_e32 v123, 0
	v_mov_b32_e32 v124, 0
	v_mov_b32_e32 v125, 0
	v_mov_b32_e32 v126, 0
	v_mov_b32_e32 v127, 0
	v_mov_b32_e32 v128, 0
	v_mov_b32_e32 v129, 0
	v_mov_b32_e32 v130, 0
	v_mov_b32_e32 v131, 0
	v_mov_b32_e32 v132, 0
	v_mov_b32_e32 v133, 0
	v_mov_b32_e32 v134, 0
	v_mov_b32_e32 v135, 0
	v_mov_b32_e32 v136, 0
	v_mov_b32_e32 v137, 0
	v_mov_b32_e32 v138, 0
	v_mov_b32_e32 v139, 0
	v_mov_b32_e32 v140, 0
	v_mov_b32_e32 v141, 0
	v_mov_b32_e32 v142, 0
	v_mov_b32_e32 v143, 0
	v_mov_b32_e32 v144, 0
	v_mov_b32_e32 v145, 0
	v_mov_b32_e32 v146, 0
	v_mov_b32_e32 v147, 0
	v_mov_b32_e32 v148, 0
	v_mov_b32_e32 v149, 0
	v_mov_b32_e32 v150, 0
	v_mov_b32_e32 v151, 0
	v_mov_b32_e32 v245, 0
	v_mov_b32_e32 v229, 0
	s_xor_b64 s[24:25], s[0:1], -1
	s_mov_b32 s0, 0
	s_mov_b32 s10, 2
	s_mov_b32 s99, 1
	s_mov_b32 s89, 0
.Lat_loop:
	s_add_i32 s18, s89, 2
	s_lshl_b32 s26, s10, 14
	s_min_u32 s18, s18, s67
	s_add_i32 s26, s96, s26
	s_lshl_b32 s18, s18, 14
	s_mov_b32 m0, s26
	s_mov_b32 s1, s89
	buffer_load_dwordx4 v240, s[28:31], s18 offen lds
	s_add_i32 m0, s26, 0x400
	s_add_i32 s89, s89, 1
	buffer_load_dwordx4 v241, s[28:31], s18 offen lds
	s_lshl_b32 s18, s99, 15
	s_min_u32 s19, s89, s67
	s_add_i32 s27, s98, s18
	s_lshl_b32 s26, s19, 15
	s_mov_b32 s18, s30
	s_mov_b32 s19, s31
	s_mov_b32 m0, s27
	s_or_b32 s84, s26, 0x80
	buffer_load_dwordx4 v242, s[16:19], s26 offen lds
	s_add_i32 m0, s27, 0x400
	v_max3_f32 v0, v160, v161, v162
	buffer_load_dwordx4 v242, s[16:19], s84 offen lds
	s_add_i32 m0, s27, 0x800
	s_or_b32 s84, s26, 0x100
	buffer_load_dwordx4 v242, s[16:19], s84 offen lds
	s_add_i32 m0, s27, 0xc00
	s_or_b32 s26, s26, 0x180
	buffer_load_dwordx4 v242, s[16:19], s26 offen lds
	v_max3_f32 v0, v0, v163, v168
	v_max3_f32 v0, v0, v169, v170
	v_max3_f32 v0, v0, v171, v176
	v_max3_f32 v0, v0, v177, v178
	v_max3_f32 v0, v0, v179, v184
	v_max3_f32 v0, v0, v185, v186
	v_max_f32_e32 v0, v0, v187
	v_max3_f32 v14, v164, v165, v166
	v_max3_f32 v14, v14, v167, v172
	v_max3_f32 v14, v14, v173, v174
	v_max3_f32 v14, v14, v175, v180
	v_max3_f32 v14, v14, v181, v182
	v_max3_f32 v14, v14, v183, v188
	v_max3_f32 v14, v14, v189, v190
	v_max_f32_e32 v14, v14, v191
	v_max_f32_e32 v15, v0, v14
	s_cmp_eq_u32 s1, 0
	s_mov_b32 s91, s0
	s_cselect_b64 s[18:19], -1, 0
	s_cmp_lg_u32 s1, 0
	s_cbranch_scc0 .Lat_resc
	s_mov_b32 s0, 0x4138aa3b
	v_cmp_ge_f32_e32 vcc, s0, v15
	s_cmp_lg_u64 vcc, exec
	s_cbranch_scc1 .Lat_resc
; #define SBAR() __builtin_amdgcn_sched_barrier(0)
; #define HBAR(n) do { asm volatile("s_waitcnt vmcnt(" #n ") lgkmcnt(0)" ::: "memory"); __builtin_amdgcn_s_barrier(); asm volatile("" ::: "memory"); } while (0)
; #define RD2(S, k, D0) do { S##l##k = tr_read<v_rd_off(D0, k, 0)>(vb); S##h##k = tr_read<v_rd_off(D0, k, 1)>(vb); } while (0)
; #define PVB(X, Y, D0, D1) do { LW(6); MF(X, 0, D0, pa0); SBAR(); RD2(Y, 0, D1); LW(6); MF(X, 1, D0, pa1); SBAR(); RD2(Y, 1, D1); \
;     LW(6); MF(X, 2, D0, pa2); SBAR(); RD2(Y, 2, D1); LW(6); MF(X, 3, D0, pa3); SBAR(); RD2(Y, 3, D1); } while (0)
; __device__ __forceinline__ void partialSM(f32x16& p0, f32x16& p1, f32x16& nm, bool first, float& alpha) {
;     ...
;     for (int r = 0; r < 16; ++r) p0[r] = __builtin_amdgcn_exp2f(p0[r]);
; }
; __device__ __forceinline__ void finishSM(f32x16& p0, f32x16& p1, float alpha, float& l_reg, bf16x8& pa0, bf16x8& pa1, bf16x8& pa2, bf16x8& pa3) {
;     float ps = 0; for (int r = 0; r < 16; ++r) ps += p0[r]; for (int r = 0; r < 16; ++r) ps += p1[r];
;     { auto rr = __builtin_amdgcn_permlane32_swap(__float_as_uint(ps), __float_as_uint(ps), false, false);
;       ps = __uint_as_float(rr[0]) + __uint_as_float(rr[1]); }
;     l_reg = l_reg * alpha + ps;
;     ...
;     PK4(p0, 0, pa0); PK4(p0, 8, pa1); PK4(p1, 0, pa2); PK4(p1, 8, pa3);
;     ...
; }
; __device__ __forceinline__ void attn_dense_body(const bf16_t* __restrict__ Qb, const bf16_t* __restrict__ Kh, const bf16_t* __restrict__ Vh,
;                                                 float* __restrict__ Ob, int seq, char* lds, LAS unsigned char* lds3, const int tid) {
;     ...
;         const int vb = vb0 + b * (int)SHM_V;
;         s16x4 Al0, Ah0, Al1, Ah1, Al2, Ah2, Al3, Ah3, Bl0, Bh0, Bl1, Bh1, Bl2, Bh2, Bl3, Bh3;
;     ...
;         HBAR(6);
;         SBAR();
;         {
;     ...
;           __builtin_amdgcn_s_setprio(1);
;           RD2(A, 0, 0); RD2(A, 1, 0); RD2(A, 2, 0); RD2(A, 3, 0);
;           PVB(A, B, 0, 1); PVB(B, A, 1, 2); PVB(A, B, 2, 3); PVB(B, A, 3, 4); PVB(A, B, 4, 5); PVB(B, A, 5, 6); PVB(A, B, 6, 7);
.Lat_exp:
	v_exp_f32_e32 v160, v160
	v_exp_f32_e32 v164, v164
	v_exp_f32_e32 v161, v161
	v_exp_f32_e32 v165, v165
	v_exp_f32_e32 v162, v162
	v_exp_f32_e32 v166, v166
	v_add_f32_e32 v0, v160, v161
	v_add_f32_e32 v14, v164, v165
	v_exp_f32_e32 v163, v163
	v_exp_f32_e32 v167, v167
	v_add_f32_e32 v0, v0, v162
	v_add_f32_e32 v14, v14, v166
	v_exp_f32_e32 v168, v168
	v_exp_f32_e32 v172, v172
	v_add_f32_e32 v0, v0, v163
	v_add_f32_e32 v14, v14, v167
	v_exp_f32_e32 v169, v169
	v_exp_f32_e32 v173, v173
	v_add_f32_e32 v0, v0, v168
	v_add_f32_e32 v14, v14, v172
	v_exp_f32_e32 v170, v170
	v_exp_f32_e32 v174, v174
	v_add_f32_e32 v0, v0, v169
	v_add_f32_e32 v14, v14, v173
	v_exp_f32_e32 v171, v171
	v_exp_f32_e32 v175, v175
	v_add_f32_e32 v0, v0, v170
	v_add_f32_e32 v14, v14, v174
	v_exp_f32_e32 v176, v176
	v_exp_f32_e32 v180, v180
	v_add_f32_e32 v0, v0, v171
	v_add_f32_e32 v14, v14, v175
	v_exp_f32_e32 v177, v177
	v_exp_f32_e32 v181, v181
	v_add_f32_e32 v0, v0, v176
	v_add_f32_e32 v14, v14, v180
	v_exp_f32_e32 v178, v178
	v_exp_f32_e32 v182, v182
	v_add_f32_e32 v0, v0, v177
	v_add_f32_e32 v14, v14, v181
	v_exp_f32_e32 v179, v179
	v_exp_f32_e32 v183, v183
	v_add_f32_e32 v0, v0, v178
	v_add_f32_e32 v14, v14, v182
	v_exp_f32_e32 v184, v184
	v_exp_f32_e32 v188, v188
	v_add_f32_e32 v0, v0, v179
	v_add_f32_e32 v14, v14, v183
	v_exp_f32_e32 v185, v185
	v_exp_f32_e32 v189, v189
	v_add_f32_e32 v0, v0, v184
	v_add_f32_e32 v14, v14, v188
	v_exp_f32_e32 v186, v186
	v_exp_f32_e32 v190, v190
	v_add_f32_e32 v0, v0, v185
	v_add_f32_e32 v14, v14, v189
	v_exp_f32_e32 v187, v187
	v_exp_f32_e32 v191, v191
	v_add_f32_e32 v0, v0, v186
	v_add_f32_e32 v14, v14, v190
	v_add_f32_e32 v0, v0, v187
	v_add_f32_e32 v14, v14, v191
	v_add_f32_e32 v245, v245, v0
	v_add_f32_e32 v229, v229, v14
	v_cvt_pk_bf16_f32 v2, v160, v161
	v_cvt_pk_bf16_f32 v3, v162, v163
	v_cvt_pk_bf16_f32 v4, v168, v169
	v_cvt_pk_bf16_f32 v5, v170, v171
	v_cvt_pk_bf16_f32 v6, v176, v177
	v_cvt_pk_bf16_f32 v7, v178, v179
	v_cvt_pk_bf16_f32 v8, v184, v185
	v_cvt_pk_bf16_f32 v9, v186, v187
	v_cvt_pk_bf16_f32 v10, v164, v165
	v_cvt_pk_bf16_f32 v11, v166, v167
	v_cvt_pk_bf16_f32 v12, v172, v173
	v_cvt_pk_bf16_f32 v13, v174, v175
	v_cvt_pk_bf16_f32 v152, v180, v181
	v_cvt_pk_bf16_f32 v153, v182, v183
	v_cvt_pk_bf16_f32 v154, v188, v189
	v_cvt_pk_bf16_f32 v155, v190, v191
	v_lshl_add_u32 v14, s91, 15, v247
	v_lshl_add_u32 v232, s99, 14, v246
	v_add_u32_e32 v0, v239, v232
	v_xad_u32 v15, v239, 64, v232
	v_xad_u32 v231, v239, s60, v232
	s_movk_i32 s0, 0xc0
	v_xad_u32 v232, v239, s0, v232
	s_nop 0
	ds_read_b64_tr_b16 v[160:161], v14 offset:0
	ds_read_b64_tr_b16 v[162:163], v14 offset:8192
	ds_read_b64_tr_b16 v[164:165], v14 offset:256
	ds_read_b64_tr_b16 v[166:167], v14 offset:8448
	ds_read_b64_tr_b16 v[168:169], v14 offset:512
	ds_read_b64_tr_b16 v[170:171], v14 offset:8704
	ds_read_b64_tr_b16 v[172:173], v14 offset:768
	ds_read_b64_tr_b16 v[174:175], v14 offset:8960
	ds_read_b64_tr_b16 v[176:177], v14 offset:1024
	ds_read_b64_tr_b16 v[178:179], v14 offset:9216
	s_waitcnt vmcnt(6) lgkmcnt(0)
	s_barrier
	s_setprio 1
	s_waitcnt lgkmcnt(8)
	v_mfma_f32_16x16x32_bf16 v[16:19], v[2:5], v[160:163], v[16:19]
	v_mfma_f32_16x16x32_bf16 v[80:83], v[10:13], v[160:163], v[80:83]
	ds_read_b64_tr_b16 v[160:161], v14 offset:16384
	ds_read_b64_tr_b16 v[162:163], v14 offset:24576
	s_waitcnt lgkmcnt(8)
	v_mfma_f32_16x16x32_bf16 v[20:23], v[2:5], v[164:167], v[20:23]
	v_mfma_f32_16x16x32_bf16 v[84:87], v[10:13], v[164:167], v[84:87]
	ds_read_b64_tr_b16 v[164:165], v14 offset:16640
	ds_read_b64_tr_b16 v[166:167], v14 offset:24832
	s_waitcnt lgkmcnt(8)
	v_mfma_f32_16x16x32_bf16 v[24:27], v[2:5], v[168:171], v[24:27]
	v_mfma_f32_16x16x32_bf16 v[88:91], v[10:13], v[168:171], v[88:91]
	ds_read_b64_tr_b16 v[168:169], v14 offset:16896
	ds_read_b64_tr_b16 v[170:171], v14 offset:25088
	s_waitcnt lgkmcnt(8)
	v_mfma_f32_16x16x32_bf16 v[28:31], v[2:5], v[172:175], v[28:31]
	v_mfma_f32_16x16x32_bf16 v[92:95], v[10:13], v[172:175], v[92:95]
	ds_read_b64_tr_b16 v[172:173], v14 offset:17152
	ds_read_b64_tr_b16 v[174:175], v14 offset:25344
	s_waitcnt lgkmcnt(8)
	v_mfma_f32_16x16x32_bf16 v[32:35], v[2:5], v[176:179], v[32:35]
	v_mfma_f32_16x16x32_bf16 v[96:99], v[10:13], v[176:179], v[96:99]
	ds_read_b64_tr_b16 v[176:177], v14 offset:17408
	ds_read_b64_tr_b16 v[178:179], v14 offset:25600
	s_waitcnt lgkmcnt(8)
	v_mfma_f32_16x16x32_bf16 v[16:19], v[6:9], v[160:163], v[16:19]
	v_mfma_f32_16x16x32_bf16 v[80:83], v[152:155], v[160:163], v[80:83]
	ds_read_b64_tr_b16 v[160:161], v14 offset:1280
	ds_read_b64_tr_b16 v[162:163], v14 offset:9472
	s_waitcnt lgkmcnt(8)
	v_mfma_f32_16x16x32_bf16 v[20:23], v[6:9], v[164:167], v[20:23]
	v_mfma_f32_16x16x32_bf16 v[84:87], v[152:155], v[164:167], v[84:87]
	ds_read_b64_tr_b16 v[164:165], v14 offset:17664
	ds_read_b64_tr_b16 v[166:167], v14 offset:25856
	s_waitcnt lgkmcnt(8)
	v_mfma_f32_16x16x32_bf16 v[24:27], v[6:9], v[168:171], v[24:27]
	v_mfma_f32_16x16x32_bf16 v[88:91], v[152:155], v[168:171], v[88:91]
	ds_read_b64_tr_b16 v[168:169], v14 offset:1536
	ds_read_b64_tr_b16 v[170:171], v14 offset:9728
	s_waitcnt lgkmcnt(8)
	v_mfma_f32_16x16x32_bf16 v[28:31], v[6:9], v[172:175], v[28:31]
	v_mfma_f32_16x16x32_bf16 v[92:95], v[152:155], v[172:175], v[92:95]
	ds_read_b64_tr_b16 v[172:173], v14 offset:17920
	ds_read_b64_tr_b16 v[174:175], v14 offset:26112
	s_waitcnt lgkmcnt(8)
	v_mfma_f32_16x16x32_bf16 v[32:35], v[6:9], v[176:179], v[32:35]
	v_mfma_f32_16x16x32_bf16 v[96:99], v[152:155], v[176:179], v[96:99]
	ds_read_b64_tr_b16 v[176:177], v14 offset:1792
	ds_read_b64_tr_b16 v[178:179], v14 offset:9984
	s_waitcnt lgkmcnt(8)
; #define SBAR() __builtin_amdgcn_sched_barrier(0)
; #define KM(d0, B0, B1) do { p0 = __builtin_amdgcn_mfma_f32_32x32x16_bf16(B0, qr[d0], p0, 0, 0, 0); p1 = __builtin_amdgcn_mfma_f32_32x32x16_bf16(B1, qr[d0], p1, 0, 0, 0); } while (0)
; #define LW(n) do { asm volatile("s_waitcnt lgkmcnt(" #n ")" ::: "memory"); SBAR(); } while (0)
; #define RD2(S, k, D0) do { S##l##k = tr_read<v_rd_off(D0, k, 0)>(vb); S##h##k = tr_read<v_rd_off(D0, k, 1)>(vb); } while (0)
; #define MF(S, k, D0, PA) do { o[D0] = __builtin_amdgcn_mfma_f32_32x32x16_bf16(PA, PKF(S##l##k, S##h##k), o[D0], 0, 0, 0); } while (0)
; #define LW(n) do { asm volatile("s_waitcnt lgkmcnt(" #n ")" ::: "memory"); SBAR(); } while (0)
; __device__ __forceinline__ void attn_dense_body(const bf16_t* __restrict__ Qb, const bf16_t* __restrict__ Kh, const bf16_t* __restrict__ Vh,
;                                                 float* __restrict__ Ob, int seq, char* lds, LAS unsigned char* lds3, const int tid) {
;     ...
;           __builtin_amdgcn_s_setprio(1);
;           RD2(A, 0, 0); RD2(A, 1, 0); RD2(A, 2, 0); RD2(A, 3, 0);
;           PVB(A, B, 0, 1); PVB(B, A, 1, 2); PVB(A, B, 2, 3); PVB(B, A, 3, 4); PVB(A, B, 4, 5); PVB(B, A, 5, 6); PVB(A, B, 6, 7);
;           const int kadr = (int)(uintptr_t)K_lds + b1 * (int)SHM_K + r32 * 256; int kt = (hi * 16) ^ ((r32 & 7) << 4);
;           asm volatile("" : "+v"(kt));
;           bf16x8 k0a, k0b, k1a, k1b, k2a, k2b;
;     ...
;           LW(6); MF(B, 0, 7, pa0); SBAR(); KRD(0, k0a, k0b);
;           LW(6); MF(B, 1, 7, pa1); SBAR(); KRD(1, k1a, k1b);
;           LW(6); MF(B, 2, 7, pa2); SBAR(); KRD(2, k2a, k2b);
;           LW(6); MF(B, 3, 7, pa3); SBAR();
;           LW(4); p0 = __builtin_amdgcn_mfma_f32_32x32x16_bf16(k0a, qr[0], nm, 0, 0, 0); p1 = __builtin_amdgcn_mfma_f32_32x32x16_bf16(k0b, qr[0], nm, 0, 0, 0); SBAR(); KRD(3, k0a, k0b);
;           LW(4); KM(1, k1a, k1b); SBAR(); KRD(4, k1a, k1b);
;           LW(4); KM(2, k2a, k2b); SBAR(); KRD(5, k2a, k2b);
;           LW(4); KM(3, k0a, k0b); SBAR(); KRD(6, k0a, k0b);
;           LW(4); KM(4, k1a, k1b); SBAR(); KRD(7, k1a, k1b);
;           LW(4); KM(5, k2a, k2b); SBAR();
;           LW(2); KM(6, k0a, k0b); SBAR();
;           LW(0); KM(7, k1a, k1b);
	v_mfma_f32_16x16x32_bf16 v[36:39], v[2:5], v[160:163], v[36:39]
	v_mfma_f32_16x16x32_bf16 v[100:103], v[10:13], v[160:163], v[100:103]
	ds_read_b64_tr_b16 v[160:161], v14 offset:18176
	ds_read_b64_tr_b16 v[162:163], v14 offset:26368
	s_waitcnt lgkmcnt(8)
	v_mfma_f32_16x16x32_bf16 v[36:39], v[6:9], v[164:167], v[36:39]
	v_mfma_f32_16x16x32_bf16 v[100:103], v[152:155], v[164:167], v[100:103]
	ds_read_b64_tr_b16 v[164:165], v14 offset:2048
	ds_read_b64_tr_b16 v[166:167], v14 offset:10240
	s_waitcnt lgkmcnt(8)
	v_mfma_f32_16x16x32_bf16 v[40:43], v[2:5], v[168:171], v[40:43]
	v_mfma_f32_16x16x32_bf16 v[104:107], v[10:13], v[168:171], v[104:107]
	ds_read_b64_tr_b16 v[168:169], v14 offset:18432
	ds_read_b64_tr_b16 v[170:171], v14 offset:26624
	s_waitcnt lgkmcnt(8)
	v_mfma_f32_16x16x32_bf16 v[40:43], v[6:9], v[172:175], v[40:43]
	v_mfma_f32_16x16x32_bf16 v[104:107], v[152:155], v[172:175], v[104:107]
	ds_read_b64_tr_b16 v[172:173], v14 offset:2304
	ds_read_b64_tr_b16 v[174:175], v14 offset:10496
	s_waitcnt lgkmcnt(8)
	v_mfma_f32_16x16x32_bf16 v[44:47], v[2:5], v[176:179], v[44:47]
	v_mfma_f32_16x16x32_bf16 v[108:111], v[10:13], v[176:179], v[108:111]
	ds_read_b64_tr_b16 v[176:177], v14 offset:18688
	ds_read_b64_tr_b16 v[178:179], v14 offset:26880
	s_waitcnt lgkmcnt(8)
	v_mfma_f32_16x16x32_bf16 v[44:47], v[6:9], v[160:163], v[44:47]
	v_mfma_f32_16x16x32_bf16 v[108:111], v[152:155], v[160:163], v[108:111]
	ds_read_b64_tr_b16 v[160:161], v14 offset:2560
	ds_read_b64_tr_b16 v[162:163], v14 offset:10752
	s_waitcnt lgkmcnt(8)
	v_mfma_f32_16x16x32_bf16 v[48:51], v[2:5], v[164:167], v[48:51]
	v_mfma_f32_16x16x32_bf16 v[112:115], v[10:13], v[164:167], v[112:115]
	ds_read_b64_tr_b16 v[164:165], v14 offset:18944
	ds_read_b64_tr_b16 v[166:167], v14 offset:27136
	s_waitcnt lgkmcnt(8)
	v_mfma_f32_16x16x32_bf16 v[48:51], v[6:9], v[168:171], v[48:51]
	v_mfma_f32_16x16x32_bf16 v[112:115], v[152:155], v[168:171], v[112:115]
	ds_read_b64_tr_b16 v[168:169], v14 offset:2816
	ds_read_b64_tr_b16 v[170:171], v14 offset:11008
	s_waitcnt lgkmcnt(8)
	v_mfma_f32_16x16x32_bf16 v[52:55], v[2:5], v[172:175], v[52:55]
	v_mfma_f32_16x16x32_bf16 v[116:119], v[10:13], v[172:175], v[116:119]
	ds_read_b64_tr_b16 v[172:173], v14 offset:19200
	ds_read_b64_tr_b16 v[174:175], v14 offset:27392
	s_waitcnt lgkmcnt(8)
	v_mfma_f32_16x16x32_bf16 v[52:55], v[6:9], v[176:179], v[52:55]
	v_mfma_f32_16x16x32_bf16 v[116:119], v[152:155], v[176:179], v[116:119]
	ds_read_b64_tr_b16 v[176:177], v14 offset:3072
	ds_read_b64_tr_b16 v[178:179], v14 offset:11264
	s_waitcnt lgkmcnt(8)
	v_mfma_f32_16x16x32_bf16 v[56:59], v[2:5], v[160:163], v[56:59]
	v_mfma_f32_16x16x32_bf16 v[120:123], v[10:13], v[160:163], v[120:123]
	ds_read_b64_tr_b16 v[160:161], v14 offset:19456
	ds_read_b64_tr_b16 v[162:163], v14 offset:27648
	s_waitcnt lgkmcnt(8)
	v_mfma_f32_16x16x32_bf16 v[56:59], v[6:9], v[164:167], v[56:59]
	v_mfma_f32_16x16x32_bf16 v[120:123], v[152:155], v[164:167], v[120:123]
	ds_read_b64_tr_b16 v[164:165], v14 offset:3328
	ds_read_b64_tr_b16 v[166:167], v14 offset:11520
	s_waitcnt lgkmcnt(8)
	v_mfma_f32_16x16x32_bf16 v[60:63], v[2:5], v[168:171], v[60:63]
	v_mfma_f32_16x16x32_bf16 v[124:127], v[10:13], v[168:171], v[124:127]
	ds_read_b64_tr_b16 v[168:169], v14 offset:19712
	ds_read_b64_tr_b16 v[170:171], v14 offset:27904
	s_waitcnt lgkmcnt(8)
	v_mfma_f32_16x16x32_bf16 v[60:63], v[6:9], v[172:175], v[60:63]
	v_mfma_f32_16x16x32_bf16 v[124:127], v[152:155], v[172:175], v[124:127]
	ds_read_b64_tr_b16 v[172:173], v14 offset:3584
	ds_read_b64_tr_b16 v[174:175], v14 offset:11776
	s_waitcnt lgkmcnt(8)
	v_mfma_f32_16x16x32_bf16 v[64:67], v[2:5], v[176:179], v[64:67]
	v_mfma_f32_16x16x32_bf16 v[128:131], v[10:13], v[176:179], v[128:131]
	ds_read_b64_tr_b16 v[176:177], v14 offset:19968
	ds_read_b64_tr_b16 v[178:179], v14 offset:28160
	s_waitcnt lgkmcnt(8)
	v_mfma_f32_16x16x32_bf16 v[64:67], v[6:9], v[160:163], v[64:67]
	v_mfma_f32_16x16x32_bf16 v[128:131], v[152:155], v[160:163], v[128:131]
	ds_read_b64_tr_b16 v[160:161], v14 offset:3840
	ds_read_b64_tr_b16 v[162:163], v14 offset:12032
	s_waitcnt lgkmcnt(8)
	v_mfma_f32_16x16x32_bf16 v[68:71], v[2:5], v[164:167], v[68:71]
	v_mfma_f32_16x16x32_bf16 v[132:135], v[10:13], v[164:167], v[132:135]
	ds_read_b64_tr_b16 v[164:165], v14 offset:20224
	ds_read_b64_tr_b16 v[166:167], v14 offset:28416
	s_waitcnt lgkmcnt(8)
	v_mfma_f32_16x16x32_bf16 v[68:71], v[6:9], v[168:171], v[68:71]
	v_mfma_f32_16x16x32_bf16 v[132:135], v[152:155], v[168:171], v[132:135]
	s_waitcnt lgkmcnt(6)
	v_mfma_f32_16x16x32_bf16 v[72:75], v[2:5], v[172:175], v[72:75]
	v_mfma_f32_16x16x32_bf16 v[136:139], v[10:13], v[172:175], v[136:139]
	ds_read_b128 v[156:159], v0 offset:0
	s_waitcnt lgkmcnt(5)
	v_mfma_f32_16x16x32_bf16 v[72:75], v[6:9], v[176:179], v[72:75]
	v_mfma_f32_16x16x32_bf16 v[136:139], v[152:155], v[176:179], v[136:139]
	ds_read_b128 v[224:227], v15 offset:0
	s_waitcnt lgkmcnt(4)
	v_mfma_f32_16x16x32_bf16 v[76:79], v[2:5], v[160:163], v[76:79]
	v_mfma_f32_16x16x32_bf16 v[140:143], v[10:13], v[160:163], v[140:143]
	ds_read_b128 v[234:237], v231 offset:0
	s_waitcnt lgkmcnt(3)
	v_mfma_f32_16x16x32_bf16 v[76:79], v[6:9], v[164:167], v[76:79]
	v_mfma_f32_16x16x32_bf16 v[140:143], v[152:155], v[164:167], v[140:143]
	ds_read_b128 v[248:251], v232 offset:0
	s_waitcnt lgkmcnt(3)
	v_mfma_f32_16x16x32_bf16 v[160:163], v[156:159], v[192:195], v[144:147]
	v_mfma_f32_16x16x32_bf16 v[164:167], v[156:159], v[208:211], v[148:151]
	ds_read_b128 v[156:159], v0 offset:4096
	s_waitcnt lgkmcnt(3)
	v_mfma_f32_16x16x32_bf16 v[160:163], v[224:227], v[196:199], v[160:163]
	v_mfma_f32_16x16x32_bf16 v[164:167], v[224:227], v[212:215], v[164:167]
	ds_read_b128 v[224:227], v15 offset:4096
	s_waitcnt lgkmcnt(3)
; #define SBAR() __builtin_amdgcn_sched_barrier(0)
; #define KM(d0, B0, B1) do { p0 = __builtin_amdgcn_mfma_f32_32x32x16_bf16(B0, qr[d0], p0, 0, 0, 0); p1 = __builtin_amdgcn_mfma_f32_32x32x16_bf16(B1, qr[d0], p1, 0, 0, 0); } while (0)
; #define HBAR(n) do { asm volatile("s_waitcnt vmcnt(" #n ") lgkmcnt(0)" ::: "memory"); __builtin_amdgcn_s_barrier(); asm volatile("" ::: "memory"); } while (0)
; #define LW(n) do { asm volatile("s_waitcnt lgkmcnt(" #n ")" ::: "memory"); SBAR(); } while (0)
; #define LW(n) do { asm volatile("s_waitcnt lgkmcnt(" #n ")" ::: "memory"); SBAR(); } while (0)
; #define KRD(d0, RA, RB) do { const int ad_ = kadr + (kt ^ ((d0) * 32)); asm volatile("ds_read_b128 %0, %1" : "=&v"(RA) : "v"(ad_) : "memory"); \
;     asm volatile("ds_read_b128 %0, %1 offset:8192" : "=&v"(RB) : "v"(ad_) : "memory"); } while (0)
; #define KM(d0, RA, RB) do { p0 = __builtin_amdgcn_mfma_f32_32x32x16_bf16(RA, qr[d0], p0, 0, 0, 0); p1 = __builtin_amdgcn_mfma_f32_32x32x16_bf16(RB, qr[d0], p1, 0, 0, 0); } while (0)
; __device__ __forceinline__ void attn_dense_body(const bf16_t* __restrict__ Qb, const bf16_t* __restrict__ Kh, const bf16_t* __restrict__ Vh,
;                                                 float* __restrict__ Ob, int seq, char* lds, LAS unsigned char* lds3, const int tid) {
;     ...
;           LW(4); p0 = __builtin_amdgcn_mfma_f32_32x32x16_bf16(k0a, qr[0], nm, 0, 0, 0); p1 = __builtin_amdgcn_mfma_f32_32x32x16_bf16(k0b, qr[0], nm, 0, 0, 0); SBAR(); KRD(3, k0a, k0b);
;           LW(4); KM(1, k1a, k1b); SBAR(); KRD(4, k1a, k1b);
;           LW(4); KM(2, k2a, k2b); SBAR(); KRD(5, k2a, k2b);
;           LW(4); KM(3, k0a, k0b); SBAR(); KRD(6, k0a, k0b);
;           LW(4); KM(4, k1a, k1b); SBAR(); KRD(7, k1a, k1b);
;           LW(4); KM(5, k2a, k2b); SBAR();
;           LW(2); KM(6, k0a, k0b); SBAR();
;           LW(0); KM(7, k1a, k1b);
;           __builtin_amdgcn_s_setprio(0);
;     ...
;         }
;     ...
;         HBAR(0);
;         { const int t_ = b; b = b1; b1 = b2; b2 = t_; }
;     }
	v_mfma_f32_16x16x32_bf16 v[160:163], v[234:237], v[200:203], v[160:163]
	v_mfma_f32_16x16x32_bf16 v[164:167], v[234:237], v[216:219], v[164:167]
	ds_read_b128 v[234:237], v231 offset:4096
	s_waitcnt lgkmcnt(3)
	v_mfma_f32_16x16x32_bf16 v[160:163], v[248:251], v[204:207], v[160:163]
	v_mfma_f32_16x16x32_bf16 v[164:167], v[248:251], v[220:223], v[164:167]
	ds_read_b128 v[248:251], v232 offset:4096
	s_waitcnt lgkmcnt(3)
	v_mfma_f32_16x16x32_bf16 v[168:171], v[156:159], v[192:195], v[144:147]
	v_mfma_f32_16x16x32_bf16 v[172:175], v[156:159], v[208:211], v[148:151]
	ds_read_b128 v[156:159], v0 offset:8192
	s_waitcnt lgkmcnt(3)
	v_mfma_f32_16x16x32_bf16 v[168:171], v[224:227], v[196:199], v[168:171]
	v_mfma_f32_16x16x32_bf16 v[172:175], v[224:227], v[212:215], v[172:175]
	ds_read_b128 v[224:227], v15 offset:8192
	s_waitcnt lgkmcnt(3)
	v_mfma_f32_16x16x32_bf16 v[168:171], v[234:237], v[200:203], v[168:171]
	v_mfma_f32_16x16x32_bf16 v[172:175], v[234:237], v[216:219], v[172:175]
	ds_read_b128 v[234:237], v231 offset:8192
	s_waitcnt lgkmcnt(3)
	v_mfma_f32_16x16x32_bf16 v[168:171], v[248:251], v[204:207], v[168:171]
	v_mfma_f32_16x16x32_bf16 v[172:175], v[248:251], v[220:223], v[172:175]
	ds_read_b128 v[248:251], v232 offset:8192
	s_waitcnt lgkmcnt(3)
	v_mfma_f32_16x16x32_bf16 v[176:179], v[156:159], v[192:195], v[144:147]
	v_mfma_f32_16x16x32_bf16 v[180:183], v[156:159], v[208:211], v[148:151]
	ds_read_b128 v[156:159], v0 offset:12288
	s_waitcnt lgkmcnt(3)
	v_mfma_f32_16x16x32_bf16 v[176:179], v[224:227], v[196:199], v[176:179]
	v_mfma_f32_16x16x32_bf16 v[180:183], v[224:227], v[212:215], v[180:183]
	ds_read_b128 v[224:227], v15 offset:12288
	s_waitcnt lgkmcnt(3)
	v_mfma_f32_16x16x32_bf16 v[176:179], v[234:237], v[200:203], v[176:179]
	v_mfma_f32_16x16x32_bf16 v[180:183], v[234:237], v[216:219], v[180:183]
	ds_read_b128 v[234:237], v231 offset:12288
	s_waitcnt lgkmcnt(3)
	v_mfma_f32_16x16x32_bf16 v[176:179], v[248:251], v[204:207], v[176:179]
	v_mfma_f32_16x16x32_bf16 v[180:183], v[248:251], v[220:223], v[180:183]
	ds_read_b128 v[248:251], v232 offset:12288
	s_waitcnt lgkmcnt(3)
	v_mfma_f32_16x16x32_bf16 v[184:187], v[156:159], v[192:195], v[144:147]
	v_mfma_f32_16x16x32_bf16 v[188:191], v[156:159], v[208:211], v[148:151]
	s_waitcnt lgkmcnt(2)
	v_mfma_f32_16x16x32_bf16 v[184:187], v[224:227], v[196:199], v[184:187]
	v_mfma_f32_16x16x32_bf16 v[188:191], v[224:227], v[212:215], v[188:191]
	s_waitcnt lgkmcnt(1)
	v_mfma_f32_16x16x32_bf16 v[184:187], v[234:237], v[200:203], v[184:187]
	v_mfma_f32_16x16x32_bf16 v[188:191], v[234:237], v[216:219], v[188:191]
	s_waitcnt lgkmcnt(0)
	v_mfma_f32_16x16x32_bf16 v[184:187], v[248:251], v[204:207], v[184:187]
	v_mfma_f32_16x16x32_bf16 v[188:191], v[248:251], v[220:223], v[188:191]
	s_setprio 0
	s_waitcnt vmcnt(0) lgkmcnt(0)
	s_barrier
	s_cmp_eq_u32 s15, s89
	s_cbranch_scc1 .Lat_done
	s_mov_b32 s0, s99
	s_mov_b32 s99, s10
	s_mov_b32 s10, s91
	s_branch .Lat_loop
; __device__ __forceinline__ void partialSM(f32x16& p0, f32x16& p1, f32x16& nm, bool first, float& alpha) {
;     ...
;     if (__builtin_expect(!first && __all(pmax <= THRL), 1)) { alpha = 1.f; }
;     else {
;         const float delta = first ? pmax : fmaxf(pmax, 0.f);
;         alpha = first ? 1.f : __builtin_amdgcn_exp2f(-delta);
;         for (int r = 0; r < 16; ++r) { p0[r] -= delta; p1[r] -= delta; nm[r] -= delta; }
;     }
.Lat_resc:
	v_mov_b32_e32 v15, v0
	s_nop 1
	v_permlane16_swap_b32_e32 v0, v15
	v_max_f32_e32 v0, v0, v15
	v_mov_b32_e32 v15, v0
	s_nop 1
	v_permlane32_swap_b32_e32 v0, v15
	v_max_f32_e32 v0, v0, v15
	v_mov_b32_e32 v15, v14
	s_nop 1
	v_permlane16_swap_b32_e32 v14, v15
	v_max_f32_e32 v14, v14, v15
	v_mov_b32_e32 v15, v14
	s_nop 1
	v_permlane32_swap_b32_e32 v14, v15
	v_max_f32_e32 v14, v14, v15
	v_max_f32_e32 v15, 0, v0
	v_max_f32_e32 v224, 0, v14
	s_nop 0
	v_cndmask_b32_e64 v0, v15, v0, s[18:19]
	v_cndmask_b32_e64 v14, v224, v14, s[18:19]
	v_exp_f32_e64 v224, -v0
	v_exp_f32_e64 v225, -v14
	s_nop 0
	v_cndmask_b32_e64 v224, v224, 1.0, s[18:19]
	v_cndmask_b32_e64 v225, v225, 1.0, s[18:19]
	v_sub_f32_e32 v160, v160, v0
	v_sub_f32_e32 v161, v161, v0
	v_sub_f32_e32 v162, v162, v0
	v_sub_f32_e32 v163, v163, v0
	v_sub_f32_e32 v168, v168, v0
	v_sub_f32_e32 v169, v169, v0
	v_sub_f32_e32 v170, v170, v0
	v_sub_f32_e32 v171, v171, v0
	v_sub_f32_e32 v176, v176, v0
	v_sub_f32_e32 v177, v177, v0
	v_sub_f32_e32 v178, v178, v0
	v_sub_f32_e32 v179, v179, v0
	v_sub_f32_e32 v184, v184, v0
	v_sub_f32_e32 v185, v185, v0
	v_sub_f32_e32 v186, v186, v0
	v_sub_f32_e32 v187, v187, v0
	v_sub_f32_e32 v164, v164, v14
	v_sub_f32_e32 v165, v165, v14
	v_sub_f32_e32 v166, v166, v14
	v_sub_f32_e32 v167, v167, v14
	v_sub_f32_e32 v172, v172, v14
	v_sub_f32_e32 v173, v173, v14
	v_sub_f32_e32 v174, v174, v14
	v_sub_f32_e32 v175, v175, v14
	v_sub_f32_e32 v180, v180, v14
	v_sub_f32_e32 v181, v181, v14
	v_sub_f32_e32 v182, v182, v14
	v_sub_f32_e32 v183, v183, v14
	v_sub_f32_e32 v188, v188, v14
	v_sub_f32_e32 v189, v189, v14
	v_sub_f32_e32 v190, v190, v14
	v_sub_f32_e32 v191, v191, v14
	v_sub_f32_e32 v144, v144, v0
	v_sub_f32_e32 v145, v145, v0
	v_sub_f32_e32 v146, v146, v0
	v_sub_f32_e32 v147, v147, v0
	v_sub_f32_e32 v148, v148, v14
	v_sub_f32_e32 v149, v149, v14
	v_sub_f32_e32 v150, v150, v14
	v_sub_f32_e32 v151, v151, v14
	v_mul_f32_e32 v245, v245, v224
	v_mul_f32_e32 v229, v229, v225
	v_min_f32_e32 v15, v224, v225
	v_cmp_gt_f32_e32 vcc, 1.0, v15
	s_cbranch_vccz .Lat_exp
	v_mbcnt_lo_u32_b32 v248, -1, 0
	v_mbcnt_hi_u32_b32 v248, -1, v248
	v_and_b32_e32 v249, 15, v248
	v_lshrrev_b32_e32 v248, 4, v248
	v_lshl_add_u32 v249, v249, 2, v243
	v_lshl_add_u32 v248, v248, 4, v243
	ds_write_b32 v249, v224 offset:128
	ds_write_b32 v249, v225 offset:192
	s_waitcnt lgkmcnt(0)
	ds_read_b128 v[156:159], v248 offset:128
	ds_read_b128 v[234:237], v248 offset:192
	s_waitcnt lgkmcnt(0)
	v_pk_mul_f32 v[16:17], v[16:17], v[156:157]
	v_pk_mul_f32 v[18:19], v[18:19], v[158:159]
	v_pk_mul_f32 v[20:21], v[20:21], v[156:157]
	v_pk_mul_f32 v[22:23], v[22:23], v[158:159]
	v_pk_mul_f32 v[24:25], v[24:25], v[156:157]
	v_pk_mul_f32 v[26:27], v[26:27], v[158:159]
	v_pk_mul_f32 v[28:29], v[28:29], v[156:157]
	v_pk_mul_f32 v[30:31], v[30:31], v[158:159]
	v_pk_mul_f32 v[32:33], v[32:33], v[156:157]
	v_pk_mul_f32 v[34:35], v[34:35], v[158:159]
	v_pk_mul_f32 v[36:37], v[36:37], v[156:157]
	v_pk_mul_f32 v[38:39], v[38:39], v[158:159]
	v_pk_mul_f32 v[40:41], v[40:41], v[156:157]
	v_pk_mul_f32 v[42:43], v[42:43], v[158:159]
	v_pk_mul_f32 v[44:45], v[44:45], v[156:157]
	v_pk_mul_f32 v[46:47], v[46:47], v[158:159]
	v_pk_mul_f32 v[48:49], v[48:49], v[156:157]
	v_pk_mul_f32 v[50:51], v[50:51], v[158:159]
	v_pk_mul_f32 v[52:53], v[52:53], v[156:157]
	v_pk_mul_f32 v[54:55], v[54:55], v[158:159]
	v_pk_mul_f32 v[56:57], v[56:57], v[156:157]
	v_pk_mul_f32 v[58:59], v[58:59], v[158:159]
	v_pk_mul_f32 v[60:61], v[60:61], v[156:157]
	v_pk_mul_f32 v[62:63], v[62:63], v[158:159]
	v_pk_mul_f32 v[64:65], v[64:65], v[156:157]
	v_pk_mul_f32 v[66:67], v[66:67], v[158:159]
	v_pk_mul_f32 v[68:69], v[68:69], v[156:157]
	v_pk_mul_f32 v[70:71], v[70:71], v[158:159]
	v_pk_mul_f32 v[72:73], v[72:73], v[156:157]
	v_pk_mul_f32 v[74:75], v[74:75], v[158:159]
	v_pk_mul_f32 v[76:77], v[76:77], v[156:157]
	v_pk_mul_f32 v[78:79], v[78:79], v[158:159]
	v_pk_mul_f32 v[80:81], v[80:81], v[234:235]
	v_pk_mul_f32 v[82:83], v[82:83], v[236:237]
	v_pk_mul_f32 v[84:85], v[84:85], v[234:235]
	v_pk_mul_f32 v[86:87], v[86:87], v[236:237]
	v_pk_mul_f32 v[88:89], v[88:89], v[234:235]
	v_pk_mul_f32 v[90:91], v[90:91], v[236:237]
	v_pk_mul_f32 v[92:93], v[92:93], v[234:235]
	v_pk_mul_f32 v[94:95], v[94:95], v[236:237]
	v_pk_mul_f32 v[96:97], v[96:97], v[234:235]
	v_pk_mul_f32 v[98:99], v[98:99], v[236:237]
	v_pk_mul_f32 v[100:101], v[100:101], v[234:235]
	v_pk_mul_f32 v[102:103], v[102:103], v[236:237]
	v_pk_mul_f32 v[104:105], v[104:105], v[234:235]
	v_pk_mul_f32 v[106:107], v[106:107], v[236:237]
	v_pk_mul_f32 v[108:109], v[108:109], v[234:235]
	v_pk_mul_f32 v[110:111], v[110:111], v[236:237]
	v_pk_mul_f32 v[112:113], v[112:113], v[234:235]
	v_pk_mul_f32 v[114:115], v[114:115], v[236:237]
	v_pk_mul_f32 v[116:117], v[116:117], v[234:235]
	v_pk_mul_f32 v[118:119], v[118:119], v[236:237]
	v_pk_mul_f32 v[120:121], v[120:121], v[234:235]
	v_pk_mul_f32 v[122:123], v[122:123], v[236:237]
	v_pk_mul_f32 v[124:125], v[124:125], v[234:235]
	v_pk_mul_f32 v[126:127], v[126:127], v[236:237]
	v_pk_mul_f32 v[128:129], v[128:129], v[234:235]
	v_pk_mul_f32 v[130:131], v[130:131], v[236:237]
	v_pk_mul_f32 v[132:133], v[132:133], v[234:235]
	v_pk_mul_f32 v[134:135], v[134:135], v[236:237]
	v_pk_mul_f32 v[136:137], v[136:137], v[234:235]
	v_pk_mul_f32 v[138:139], v[138:139], v[236:237]
	v_pk_mul_f32 v[140:141], v[140:141], v[234:235]
	v_pk_mul_f32 v[142:143], v[142:143], v[236:237]
	s_branch .Lat_exp

; __device__ __forceinline__ int fresh_lane() { int l; asm volatile("v_mbcnt_lo_u32_b32 %0, -1, 0\n\tv_mbcnt_hi_u32_b32 %0, -1, %0" : "=v"(l)); return l; }
; __device__ __forceinline__ int crow(int r, int hi) { return (r & 3) + 8 * (r >> 2) + 4 * hi; }
; __device__ __forceinline__ void attn_dense_body(const bf16_t* __restrict__ Qb, const bf16_t* __restrict__ Kh, const bf16_t* __restrict__ Vh,
;                                                 float* __restrict__ Ob, int seq, char* lds, LAS unsigned char* lds3, const int tid) {
;     ...
;     if (DESYNC && half == 0) { __builtin_amdgcn_s_barrier(); asm volatile("" ::: "memory"); }
;     __builtin_amdgcn_s_setprio(0);
;     asm volatile("s_waitcnt vmcnt(0)" ::: "memory");
;     const int le = fresh_lane();
;     const int r32e = le & 31, hie = le >> 5;
;     float* lie = (float*)(lds + WS_OFF) + wid * 64;
;     if (hie == 0) lie[r32e] = l_reg; asm volatile("s_waitcnt lgkmcnt(0)" ::: "memory");
;     const unsigned ob = (unsigned)(wid * QBLK * LDO + r32e);
; #pragma unroll
;     for (int r = 0; r < 16; ++r) { const int orow = crow(r, hie); const float rl = __builtin_amdgcn_rcpf(lie[orow]);
; #pragma unroll
;         for (int d0 = 0; d0 < 8; ++d0) Ob[ob + (unsigned)(orow * LDO + d0 * 32)] = o[d0][r] * rl; }
.Lat_stag2:
	s_or_b64 exec, exec, s[0:1]
	s_setprio 0
	s_waitcnt vmcnt(0)
	v_mov_b32_e32 v15, v245
	s_nop 1
	v_permlane16_swap_b32_e32 v245, v15
	v_add_f32_e32 v245, v245, v15
	v_mov_b32_e32 v15, v245
	s_nop 1
	v_permlane32_swap_b32_e32 v245, v15
	v_add_f32_e32 v245, v245, v15
	v_mov_b32_e32 v15, v229
	s_nop 1
	v_permlane16_swap_b32_e32 v229, v15
	v_add_f32_e32 v229, v229, v15
	v_mov_b32_e32 v15, v229
	s_nop 1
	v_permlane32_swap_b32_e32 v229, v15
	v_add_f32_e32 v229, v229, v15
	v_mbcnt_lo_u32_b32 v248, -1, 0
	v_mbcnt_hi_u32_b32 v248, -1, v248
	v_and_b32_e32 v249, 15, v248
	v_lshrrev_b32_e32 v248, 4, v248
	v_lshl_add_u32 v249, v249, 2, v243
	v_lshl_add_u32 v248, v248, 4, v243
	ds_write_b32 v249, v245
	ds_write_b32 v249, v229 offset:64
	s_waitcnt lgkmcnt(0)
	ds_read_b128 v[2:5], v248
	ds_read_b128 v[6:9], v248 offset:64
	v_mbcnt_lo_u32_b32 v10, -1, 0
	v_mbcnt_hi_u32_b32 v10, -1, v10
	v_and_b32_e32 v12, 15, v10
	v_lshrrev_b32_e32 v10, 4, v10
	v_lshlrev_b32_e32 v13, 5, v238
	v_lshl_add_u32 v10, v10, 2, v13
	v_lshl_or_b32 v10, v10, 8, v12
	v_mov_b32_e32 v11, v1
	s_lshl_b32 s50, s50, 16
	s_lshl_b64 s[0:1], s[50:51], 2
	s_add_u32 s18, s22, s0
	s_addc_u32 s19, s23, s1
	v_lshl_add_u64 v[12:13], v[10:11], 2, s[18:19]
	v_add_u32_e32 v10, 0x1000, v10
	v_lshl_add_u64 v[14:15], v[10:11], 2, s[18:19]
	s_waitcnt lgkmcnt(0)
	v_rcp_f32_e32 v2, v2
	v_rcp_f32_e32 v3, v3
	v_rcp_f32_e32 v4, v4
	v_rcp_f32_e32 v5, v5
	v_rcp_f32_e32 v6, v6
	v_rcp_f32_e32 v7, v7
	v_rcp_f32_e32 v8, v8
	v_rcp_f32_e32 v9, v9
	s_nop 0
	v_mul_f32_e32 v224, v16, v2
	global_store_dword v[12:13], v224, off
	v_mul_f32_e32 v225, v17, v3
	global_store_dword v[12:13], v225, off offset:1024
	v_mul_f32_e32 v226, v18, v4
	global_store_dword v[12:13], v226, off offset:2048
	v_mul_f32_e32 v234, v19, v5
	global_store_dword v[12:13], v234, off offset:3072
	v_mul_f32_e32 v235, v20, v2
	global_store_dword v[12:13], v235, off offset:64
	v_mul_f32_e32 v236, v21, v3
	global_store_dword v[12:13], v236, off offset:1088
	v_mul_f32_e32 v237, v22, v4
	global_store_dword v[12:13], v237, off offset:2112
	v_mul_f32_e32 v248, v23, v5
	global_store_dword v[12:13], v248, off offset:3136
	v_mul_f32_e32 v224, v24, v2
	global_store_dword v[12:13], v224, off offset:128
	v_mul_f32_e32 v225, v25, v3
	global_store_dword v[12:13], v225, off offset:1152
	v_mul_f32_e32 v226, v26, v4
	global_store_dword v[12:13], v226, off offset:2176
	v_mul_f32_e32 v234, v27, v5
	global_store_dword v[12:13], v234, off offset:3200
	v_mul_f32_e32 v235, v28, v2
	global_store_dword v[12:13], v235, off offset:192
	v_mul_f32_e32 v236, v29, v3
	global_store_dword v[12:13], v236, off offset:1216
	v_mul_f32_e32 v237, v30, v4
	global_store_dword v[12:13], v237, off offset:2240
	v_mul_f32_e32 v248, v31, v5
	global_store_dword v[12:13], v248, off offset:3264
	v_mul_f32_e32 v224, v32, v2
	global_store_dword v[12:13], v224, off offset:256
	v_mul_f32_e32 v225, v33, v3
	global_store_dword v[12:13], v225, off offset:1280
	v_mul_f32_e32 v226, v34, v4
	global_store_dword v[12:13], v226, off offset:2304
	v_mul_f32_e32 v234, v35, v5
	global_store_dword v[12:13], v234, off offset:3328
	v_mul_f32_e32 v235, v36, v2
	global_store_dword v[12:13], v235, off offset:320
	v_mul_f32_e32 v236, v37, v3
	global_store_dword v[12:13], v236, off offset:1344
	v_mul_f32_e32 v237, v38, v4
	global_store_dword v[12:13], v237, off offset:2368
	v_mul_f32_e32 v248, v39, v5
	global_store_dword v[12:13], v248, off offset:3392
	v_mul_f32_e32 v224, v40, v2
	global_store_dword v[12:13], v224, off offset:384
	v_mul_f32_e32 v225, v41, v3
	global_store_dword v[12:13], v225, off offset:1408
	v_mul_f32_e32 v226, v42, v4
	global_store_dword v[12:13], v226, off offset:2432
	v_mul_f32_e32 v234, v43, v5
	global_store_dword v[12:13], v234, off offset:3456
	v_mul_f32_e32 v235, v44, v2
	global_store_dword v[12:13], v235, off offset:448
	v_mul_f32_e32 v236, v45, v3
	global_store_dword v[12:13], v236, off offset:1472
	v_mul_f32_e32 v237, v46, v4
	global_store_dword v[12:13], v237, off offset:2496
	v_mul_f32_e32 v248, v47, v5
	global_store_dword v[12:13], v248, off offset:3520
	v_mul_f32_e32 v224, v48, v2
	global_store_dword v[12:13], v224, off offset:512
	v_mul_f32_e32 v225, v49, v3
	global_store_dword v[12:13], v225, off offset:1536
	v_mul_f32_e32 v226, v50, v4
	global_store_dword v[12:13], v226, off offset:2560
	v_mul_f32_e32 v234, v51, v5
	global_store_dword v[12:13], v234, off offset:3584
	v_mul_f32_e32 v235, v52, v2
	global_store_dword v[12:13], v235, off offset:576
	v_mul_f32_e32 v236, v53, v3
	global_store_dword v[12:13], v236, off offset:1600
	v_mul_f32_e32 v237, v54, v4
	global_store_dword v[12:13], v237, off offset:2624
	v_mul_f32_e32 v248, v55, v5
	global_store_dword v[12:13], v248, off offset:3648
	v_mul_f32_e32 v224, v56, v2
	global_store_dword v[12:13], v224, off offset:640
	v_mul_f32_e32 v225, v57, v3
	global_store_dword v[12:13], v225, off offset:1664
	v_mul_f32_e32 v226, v58, v4
	global_store_dword v[12:13], v226, off offset:2688
	v_mul_f32_e32 v234, v59, v5
	global_store_dword v[12:13], v234, off offset:3712
	v_mul_f32_e32 v235, v60, v2
	global_store_dword v[12:13], v235, off offset:704
	v_mul_f32_e32 v236, v61, v3
	global_store_dword v[12:13], v236, off offset:1728
	v_mul_f32_e32 v237, v62, v4
	global_store_dword v[12:13], v237, off offset:2752
	v_mul_f32_e32 v248, v63, v5
	global_store_dword v[12:13], v248, off offset:3776
	v_mul_f32_e32 v224, v64, v2
	global_store_dword v[12:13], v224, off offset:768
	v_mul_f32_e32 v225, v65, v3
	global_store_dword v[12:13], v225, off offset:1792
	v_mul_f32_e32 v226, v66, v4
	global_store_dword v[12:13], v226, off offset:2816
	v_mul_f32_e32 v234, v67, v5
; #define LAS __attribute__((address_space(3)))
; __device__ __forceinline__ int crow(int r, int hi) { return (r & 3) + 8 * (r >> 2) + 4 * hi; }
; __device__ __forceinline__ void attn_dense_body(const bf16_t* __restrict__ Qb, const bf16_t* __restrict__ Kh, const bf16_t* __restrict__ Vh,
;                                                 float* __restrict__ Ob, int seq, char* lds, LAS unsigned char* lds3, const int tid) {
;     ...
;     for (int r = 0; r < 16; ++r) { const int orow = crow(r, hie); const float rl = __builtin_amdgcn_rcpf(lie[orow]);
; #pragma unroll
;         for (int d0 = 0; d0 < 8; ++d0) Ob[ob + (unsigned)(orow * LDO + d0 * 32)] = o[d0][r] * rl; }
; __device__ __forceinline__ void attn_phase(const int tid, PRef p, int layer, char* lds) {
;     ...
;         for (int c = 0; c < 2; ++c)
;             att::attn_dense_body(Qp + (size_t)c * sq * 128, Kp + (size_t)c * SKV * 128, Vp, scr + c * 65536, seq, lds, (LAS unsigned char*)lds, tid);
	global_store_dword v[12:13], v234, off offset:3840
	v_mul_f32_e32 v235, v68, v2
	global_store_dword v[12:13], v235, off offset:832
	v_mul_f32_e32 v236, v69, v3
	global_store_dword v[12:13], v236, off offset:1856
	v_mul_f32_e32 v237, v70, v4
	global_store_dword v[12:13], v237, off offset:2880
	v_mul_f32_e32 v248, v71, v5
	global_store_dword v[12:13], v248, off offset:3904
	v_mul_f32_e32 v224, v72, v2
	global_store_dword v[12:13], v224, off offset:896
	v_mul_f32_e32 v225, v73, v3
	global_store_dword v[12:13], v225, off offset:1920
	v_mul_f32_e32 v226, v74, v4
	global_store_dword v[12:13], v226, off offset:2944
	v_mul_f32_e32 v234, v75, v5
	global_store_dword v[12:13], v234, off offset:3968
	v_mul_f32_e32 v235, v76, v2
	global_store_dword v[12:13], v235, off offset:960
	v_mul_f32_e32 v236, v77, v3
	global_store_dword v[12:13], v236, off offset:1984
	v_mul_f32_e32 v237, v78, v4
	global_store_dword v[12:13], v237, off offset:3008
	v_mul_f32_e32 v248, v79, v5
	global_store_dword v[12:13], v248, off offset:4032
	v_mul_f32_e32 v224, v80, v6
	global_store_dword v[14:15], v224, off
	v_mul_f32_e32 v225, v81, v7
	global_store_dword v[14:15], v225, off offset:1024
	v_mul_f32_e32 v226, v82, v8
	global_store_dword v[14:15], v226, off offset:2048
	v_mul_f32_e32 v234, v83, v9
	global_store_dword v[14:15], v234, off offset:3072
	v_mul_f32_e32 v235, v84, v6
	global_store_dword v[14:15], v235, off offset:64
	v_mul_f32_e32 v236, v85, v7
	global_store_dword v[14:15], v236, off offset:1088
	v_mul_f32_e32 v237, v86, v8
	global_store_dword v[14:15], v237, off offset:2112
	v_mul_f32_e32 v248, v87, v9
	global_store_dword v[14:15], v248, off offset:3136
	v_mul_f32_e32 v224, v88, v6
	global_store_dword v[14:15], v224, off offset:128
	v_mul_f32_e32 v225, v89, v7
	global_store_dword v[14:15], v225, off offset:1152
	v_mul_f32_e32 v226, v90, v8
	global_store_dword v[14:15], v226, off offset:2176
	v_mul_f32_e32 v234, v91, v9
	global_store_dword v[14:15], v234, off offset:3200
	v_mul_f32_e32 v235, v92, v6
	global_store_dword v[14:15], v235, off offset:192
	v_mul_f32_e32 v236, v93, v7
	global_store_dword v[14:15], v236, off offset:1216
	v_mul_f32_e32 v237, v94, v8
	global_store_dword v[14:15], v237, off offset:2240
	v_mul_f32_e32 v248, v95, v9
	global_store_dword v[14:15], v248, off offset:3264
	v_mul_f32_e32 v224, v96, v6
	global_store_dword v[14:15], v224, off offset:256
	v_mul_f32_e32 v225, v97, v7
	global_store_dword v[14:15], v225, off offset:1280
	v_mul_f32_e32 v226, v98, v8
	global_store_dword v[14:15], v226, off offset:2304
	v_mul_f32_e32 v234, v99, v9
	global_store_dword v[14:15], v234, off offset:3328
	v_mul_f32_e32 v235, v100, v6
	global_store_dword v[14:15], v235, off offset:320
	v_mul_f32_e32 v236, v101, v7
	global_store_dword v[14:15], v236, off offset:1344
	v_mul_f32_e32 v237, v102, v8
	global_store_dword v[14:15], v237, off offset:2368
	v_mul_f32_e32 v248, v103, v9
	global_store_dword v[14:15], v248, off offset:3392
	v_mul_f32_e32 v224, v104, v6
	global_store_dword v[14:15], v224, off offset:384
	v_mul_f32_e32 v225, v105, v7
	global_store_dword v[14:15], v225, off offset:1408
	v_mul_f32_e32 v226, v106, v8
	global_store_dword v[14:15], v226, off offset:2432
	v_mul_f32_e32 v234, v107, v9
	global_store_dword v[14:15], v234, off offset:3456
	v_mul_f32_e32 v235, v108, v6
	global_store_dword v[14:15], v235, off offset:448
	v_mul_f32_e32 v236, v109, v7
	global_store_dword v[14:15], v236, off offset:1472
	v_mul_f32_e32 v237, v110, v8
	global_store_dword v[14:15], v237, off offset:2496
	v_mul_f32_e32 v248, v111, v9
	global_store_dword v[14:15], v248, off offset:3520
	v_mul_f32_e32 v224, v112, v6
	global_store_dword v[14:15], v224, off offset:512
	v_mul_f32_e32 v225, v113, v7
	global_store_dword v[14:15], v225, off offset:1536
	v_mul_f32_e32 v226, v114, v8
	global_store_dword v[14:15], v226, off offset:2560
	v_mul_f32_e32 v234, v115, v9
	global_store_dword v[14:15], v234, off offset:3584
	v_mul_f32_e32 v235, v116, v6
	global_store_dword v[14:15], v235, off offset:576
	v_mul_f32_e32 v236, v117, v7
	global_store_dword v[14:15], v236, off offset:1600
	v_mul_f32_e32 v237, v118, v8
	global_store_dword v[14:15], v237, off offset:2624
	v_mul_f32_e32 v248, v119, v9
	global_store_dword v[14:15], v248, off offset:3648
	v_mul_f32_e32 v224, v120, v6
	global_store_dword v[14:15], v224, off offset:640
	v_mul_f32_e32 v225, v121, v7
	global_store_dword v[14:15], v225, off offset:1664
	v_mul_f32_e32 v226, v122, v8
	global_store_dword v[14:15], v226, off offset:2688
	v_mul_f32_e32 v234, v123, v9
	global_store_dword v[14:15], v234, off offset:3712
	v_mul_f32_e32 v235, v124, v6
	global_store_dword v[14:15], v235, off offset:704
	v_mul_f32_e32 v236, v125, v7
	global_store_dword v[14:15], v236, off offset:1728
	v_mul_f32_e32 v237, v126, v8
	global_store_dword v[14:15], v237, off offset:2752
	v_mul_f32_e32 v248, v127, v9
	global_store_dword v[14:15], v248, off offset:3776
	v_mul_f32_e32 v224, v128, v6
	global_store_dword v[14:15], v224, off offset:768
	v_mul_f32_e32 v225, v129, v7
	global_store_dword v[14:15], v225, off offset:1792
	v_mul_f32_e32 v226, v130, v8
	global_store_dword v[14:15], v226, off offset:2816
	v_mul_f32_e32 v234, v131, v9
	global_store_dword v[14:15], v234, off offset:3840
	v_mul_f32_e32 v235, v132, v6
	global_store_dword v[14:15], v235, off offset:832
	v_mul_f32_e32 v236, v133, v7
	global_store_dword v[14:15], v236, off offset:1856
	v_mul_f32_e32 v237, v134, v8
	global_store_dword v[14:15], v237, off offset:2880
	v_mul_f32_e32 v248, v135, v9
	global_store_dword v[14:15], v248, off offset:3904
	v_mul_f32_e32 v224, v136, v6
	global_store_dword v[14:15], v224, off offset:896
	v_mul_f32_e32 v225, v137, v7
	global_store_dword v[14:15], v225, off offset:1920
	v_mul_f32_e32 v226, v138, v8
	global_store_dword v[14:15], v226, off offset:2944
	v_mul_f32_e32 v234, v139, v9
	global_store_dword v[14:15], v234, off offset:3968
	v_mul_f32_e32 v235, v140, v6
	global_store_dword v[14:15], v235, off offset:960
	v_mul_f32_e32 v236, v141, v7
	global_store_dword v[14:15], v236, off offset:1984
	v_mul_f32_e32 v237, v142, v8
	global_store_dword v[14:15], v237, off offset:3008
	v_mul_f32_e32 v248, v143, v9
	global_store_dword v[14:15], v248, off offset:4032
	s_mov_b32 s50, 1
	s_mov_b64 s[0:1], 0
	s_and_b64 vcc, exec, s[24:25]
	s_cbranch_vccnz .LBB0_236
	s_branch .LBB0_215
